# weight prep w_qkv item: norm-scale loads batched
# speedup vs baseline: 1.0075x; 1.0038x over previous
.LBB0_836:
	v_mov_b32_e32 v16, s47
	v_mov_b32_e32 v17, s36
	v_cmp_gt_i32_e32 vcc, s37, v112
	s_nop 1
	v_cndmask_b32_e32 v16, v16, v17, vcc
	v_add_u32_e32 v19, v16, v112
	v_cmp_lt_i32_e32 vcc, s59, v19
	s_and_saveexec_b64 s[6:7], vcc
	s_xor_b64 s[22:23], exec, s[6:7]
	s_cbranch_execz .LBB0_866
	s_movk_i32 s0, 0x43ff
	v_cmp_lt_u32_e32 vcc, s0, v19
	s_and_saveexec_b64 s[6:7], vcc
	s_xor_b64 s[6:7], exec, s[6:7]
	s_cbranch_execz .LBB0_851
	s_movk_i32 s0, 0x45ff
	v_cmp_lt_u32_e32 vcc, s0, v19
	s_and_saveexec_b64 s[8:9], vcc
	s_xor_b64 s[8:9], exec, s[8:9]
	s_cbranch_execz .LBB0_848
	s_movk_i32 s0, 0x47ff
	v_cmp_lt_u32_e32 vcc, s0, v19
	s_and_saveexec_b64 s[10:11], vcc
	s_xor_b64 s[10:11], exec, s[10:11]
	s_cbranch_execz .LBB0_845
	s_movk_i32 s0, 0x49ff
	v_cmp_lt_u32_e32 vcc, s0, v19
	s_and_saveexec_b64 s[24:25], vcc
	s_xor_b64 s[24:25], exec, s[24:25]
	s_cbranch_execz .LBB0_842
	v_add_u32_e32 v16, 0xffffb600, v19
	s_mov_b32 s0, 0xaaaaaaab
	v_mul_hi_u32 v17, v16, s0
	s_load_dwordx2 s[50:51], s[92:93], 0x88
	s_load_dwordx2 s[28:29], s[92:93], 0x28
	v_lshrrev_b32_e32 v18, 6, v17
	s_movk_i32 s0, 0x60
	v_mul_lo_u32 v18, v18, s0
	v_sub_u32_e32 v18, v16, v18
	v_lshlrev_b32_e32 v158, 5, v18
	v_and_b32_e32 v16, 0xffffffc0, v17
	s_waitcnt lgkmcnt(0)
	v_lshl_add_u64 v[20:21], v[158:159], 2, s[50:51]
	v_lshlrev_b32_e32 v22, 2, v2
	v_mov_b32_e32 v23, v159
	v_or_b32_e32 v18, v16, v0
	v_lshl_add_u64 v[30:31], v[20:21], 0, v[22:23]
	s_movk_i32 s0, 0x3000
	v_mad_u64_u32 v[20:21], s[50:51], v18, s0, v[30:31]
	v_or_b32_e32 v17, 2, v18
	global_load_dword v34, v[20:21], off nt
	v_mad_u64_u32 v[20:21], s[50:51], v17, s0, v[30:31]
	v_or_b32_e32 v17, 4, v18
	global_load_dword v35, v[20:21], off nt
	v_mad_u64_u32 v[20:21], s[50:51], v17, s0, v[30:31]
	v_or_b32_e32 v17, 6, v18
	global_load_dword v36, v[20:21], off nt
	v_mad_u64_u32 v[20:21], s[50:51], v17, s0, v[30:31]
	v_or_b32_e32 v17, 8, v18
	global_load_dword v37, v[20:21], off nt
	v_mad_u64_u32 v[20:21], s[50:51], v17, s0, v[30:31]
	v_or_b32_e32 v17, 10, v18
	global_load_dword v38, v[20:21], off nt
	v_mad_u64_u32 v[20:21], s[50:51], v17, s0, v[30:31]
	v_or_b32_e32 v17, 12, v18
	global_load_dword v39, v[20:21], off nt
	v_mad_u64_u32 v[20:21], s[50:51], v17, s0, v[30:31]
	v_or_b32_e32 v17, 14, v18
	global_load_dword v40, v[20:21], off nt
	v_mad_u64_u32 v[20:21], s[50:51], v17, s0, v[30:31]
	v_or_b32_e32 v17, 16, v18
	global_load_dword v41, v[20:21], off nt
	v_mad_u64_u32 v[20:21], s[50:51], v17, s0, v[30:31]
	v_or_b32_e32 v17, 18, v18
	global_load_dword v113, v[20:21], off nt
	v_mad_u64_u32 v[20:21], s[50:51], v17, s0, v[30:31]
	v_or_b32_e32 v17, 20, v18
	global_load_dword v114, v[20:21], off nt
	v_mad_u64_u32 v[20:21], s[50:51], v17, s0, v[30:31]
	v_or_b32_e32 v17, 22, v18
	global_load_dword v115, v[20:21], off nt
	v_mad_u64_u32 v[20:21], s[50:51], v17, s0, v[30:31]
	v_or_b32_e32 v17, 24, v18
	global_load_dword v116, v[20:21], off nt
	v_mad_u64_u32 v[20:21], s[50:51], v17, s0, v[30:31]
	v_or_b32_e32 v17, 26, v18
	global_load_dword v117, v[20:21], off nt
	v_mad_u64_u32 v[20:21], s[50:51], v17, s0, v[30:31]
	v_or_b32_e32 v17, 28, v18
	global_load_dword v118, v[20:21], off nt
	v_mad_u64_u32 v[20:21], s[50:51], v17, s0, v[30:31]
	v_or_b32_e32 v17, 30, v18
	global_load_dword v119, v[20:21], off nt
	v_mad_u64_u32 v[20:21], s[50:51], v17, s0, v[30:31]
	v_or_b32_e32 v17, 32, v18
	global_load_dword v120, v[20:21], off nt
	v_mad_u64_u32 v[20:21], s[50:51], v17, s0, v[30:31]
	v_or_b32_e32 v17, 34, v18
	global_load_dword v121, v[20:21], off nt
	v_mad_u64_u32 v[20:21], s[50:51], v17, s0, v[30:31]
	v_or_b32_e32 v17, 36, v18
	global_load_dword v122, v[20:21], off nt
	v_mad_u64_u32 v[20:21], s[50:51], v17, s0, v[30:31]
	v_or_b32_e32 v17, 38, v18
	global_load_dword v123, v[20:21], off nt
	v_mad_u64_u32 v[20:21], s[50:51], v17, s0, v[30:31]
	v_or_b32_e32 v17, 40, v18
	global_load_dword v124, v[20:21], off nt
	v_mad_u64_u32 v[20:21], s[50:51], v17, s0, v[30:31]
	v_or_b32_e32 v17, 42, v18
	global_load_dword v125, v[20:21], off nt
	v_mad_u64_u32 v[20:21], s[50:51], v17, s0, v[30:31]
	v_or_b32_e32 v17, 44, v18
	global_load_dword v29, v[20:21], off nt
	v_mad_u64_u32 v[20:21], s[50:51], v17, s0, v[30:31]
	v_or_b32_e32 v17, 46, v18
	global_load_dword v28, v[20:21], off nt
	v_mad_u64_u32 v[20:21], s[50:51], v17, s0, v[30:31]
	v_or_b32_e32 v17, 48, v18
	global_load_dword v27, v[20:21], off nt
	v_mad_u64_u32 v[20:21], s[50:51], v17, s0, v[30:31]
	v_or_b32_e32 v17, 50, v18
	global_load_dword v26, v[20:21], off nt
	v_mad_u64_u32 v[20:21], s[50:51], v17, s0, v[30:31]
	v_or_b32_e32 v17, 52, v18
	global_load_dword v25, v[20:21], off nt
	v_mad_u64_u32 v[20:21], s[50:51], v17, s0, v[30:31]
	v_or_b32_e32 v17, 54, v18
	global_load_dword v24, v[20:21], off nt
	v_mad_u64_u32 v[20:21], s[50:51], v17, s0, v[30:31]
	v_or_b32_e32 v17, 56, v18
	s_add_u32 s28, s28, 0x1000
	global_load_dword v23, v[20:21], off nt
	v_mad_u64_u32 v[20:21], s[50:51], v17, s0, v[30:31]
	v_or_b32_e32 v17, 58, v18
	s_addc_u32 s29, s29, 0
	v_mov_b32_e32 v19, v159
	global_load_dword v22, v[20:21], off nt
	v_mad_u64_u32 v[20:21], s[50:51], v17, s0, v[30:31]
	v_or_b32_e32 v17, 60, v18
	v_mad_u64_u32 v[32:33], s[50:51], v17, s0, v[30:31]
	v_or_b32_e32 v17, 62, v18
	v_lshl_add_u64 v[18:19], v[18:19], 2, s[28:29]
	global_load_dword v214, v[18:19], off
	v_mov_b32_e32 v19, v159
	global_load_dword v21, v[20:21], off nt
	v_mad_u64_u32 v[30:31], s[50:51], v17, s0, v[30:31]
	global_load_dword v17, v[30:31], off nt
	global_load_dword v20, v[32:33], off nt
	v_or_b32_e32 v18, v16, v45
	v_lshl_add_u64 v[18:19], v[18:19], 2, s[28:29]
	global_load_dword v215, v[18:19], off
	v_mov_b32_e32 v19, v159
	v_or_b32_e32 v18, v16, v47
	v_lshl_add_u64 v[18:19], v[18:19], 2, s[28:29]
	global_load_dword v216, v[18:19], off
	v_mov_b32_e32 v19, v159
	v_or_b32_e32 v18, v16, v49
	v_lshl_add_u64 v[18:19], v[18:19], 2, s[28:29]
	global_load_dword v217, v[18:19], off
	v_mov_b32_e32 v19, v159
	v_or_b32_e32 v18, v16, v51
	v_lshl_add_u64 v[18:19], v[18:19], 2, s[28:29]
	global_load_dword v218, v[18:19], off
	v_mov_b32_e32 v19, v159
	v_or_b32_e32 v18, v16, v53
	v_lshl_add_u64 v[18:19], v[18:19], 2, s[28:29]
	global_load_dword v219, v[18:19], off
	v_mov_b32_e32 v19, v159
	v_or_b32_e32 v18, v16, v55
	v_lshl_add_u64 v[18:19], v[18:19], 2, s[28:29]
	global_load_dword v220, v[18:19], off
	v_mov_b32_e32 v19, v159
	v_or_b32_e32 v18, v16, v57
	v_lshl_add_u64 v[18:19], v[18:19], 2, s[28:29]
	global_load_dword v221, v[18:19], off
	v_mov_b32_e32 v19, v159
	v_or_b32_e32 v18, v16, v59
	v_lshl_add_u64 v[18:19], v[18:19], 2, s[28:29]
	global_load_dword v222, v[18:19], off
	v_mov_b32_e32 v19, v159
	v_or_b32_e32 v18, v16, v61
	v_lshl_add_u64 v[18:19], v[18:19], 2, s[28:29]
	global_load_dword v223, v[18:19], off
	v_mov_b32_e32 v19, v159
	v_or_b32_e32 v18, v16, v63
	v_lshl_add_u64 v[18:19], v[18:19], 2, s[28:29]
	global_load_dword v224, v[18:19], off
	v_mov_b32_e32 v19, v159
	v_or_b32_e32 v18, v16, v65
	v_lshl_add_u64 v[18:19], v[18:19], 2, s[28:29]
	global_load_dword v225, v[18:19], off
	v_mov_b32_e32 v19, v159
	v_or_b32_e32 v18, v16, v67
	v_lshl_add_u64 v[18:19], v[18:19], 2, s[28:29]
	global_load_dword v226, v[18:19], off
	v_mov_b32_e32 v19, v159
	v_or_b32_e32 v18, v16, v69
	v_lshl_add_u64 v[18:19], v[18:19], 2, s[28:29]
	global_load_dword v227, v[18:19], off
	v_mov_b32_e32 v19, v159
	v_or_b32_e32 v18, v16, v71
	v_lshl_add_u64 v[18:19], v[18:19], 2, s[28:29]
	global_load_dword v228, v[18:19], off
	v_mov_b32_e32 v19, v159
	v_or_b32_e32 v18, v16, v73
	v_lshl_add_u64 v[18:19], v[18:19], 2, s[28:29]
	global_load_dword v229, v[18:19], off
	v_mov_b32_e32 v19, v159
	s_waitcnt vmcnt(0)
	v_mul_f32_e32 v18, v34, v214
	ds_write_b32 v44, v18
	v_mul_f32_e32 v18, v35, v215
	ds_write_b32 v46, v18
	v_mul_f32_e32 v18, v36, v216
	ds_write_b32 v48, v18
	v_mul_f32_e32 v18, v37, v217
	ds_write_b32 v50, v18
	v_mul_f32_e32 v18, v38, v218
	ds_write_b32 v52, v18
	v_mul_f32_e32 v18, v39, v219
	ds_write_b32 v54, v18
	v_mul_f32_e32 v18, v40, v220
	ds_write_b32 v56, v18
	v_mul_f32_e32 v18, v41, v221
	ds_write_b32 v58, v18
	v_mul_f32_e32 v18, v113, v222
	ds_write_b32 v60, v18
	v_mul_f32_e32 v18, v114, v223
	ds_write_b32 v62, v18
	v_mul_f32_e32 v18, v115, v224
	ds_write_b32 v64, v18
	v_mul_f32_e32 v18, v116, v225
	ds_write_b32 v66, v18
	v_mul_f32_e32 v18, v117, v226
	ds_write_b32 v68, v18
	v_mul_f32_e32 v18, v118, v227
	ds_write_b32 v70, v18
	v_mul_f32_e32 v18, v119, v228
	ds_write_b32 v72, v18
	v_mul_f32_e32 v18, v120, v229
	ds_write_b32 v74, v18
	v_or_b32_e32 v18, v16, v75
	v_lshl_add_u64 v[18:19], v[18:19], 2, s[28:29]
	global_load_dword v230, v[18:19], off
	v_mov_b32_e32 v19, v159
	v_or_b32_e32 v18, v16, v77
	v_lshl_add_u64 v[18:19], v[18:19], 2, s[28:29]
	global_load_dword v231, v[18:19], off
	v_mov_b32_e32 v19, v159
	v_or_b32_e32 v18, v16, v79
	v_lshl_add_u64 v[18:19], v[18:19], 2, s[28:29]
	global_load_dword v232, v[18:19], off
	v_mov_b32_e32 v19, v159
	v_or_b32_e32 v18, v16, v81
	v_lshl_add_u64 v[18:19], v[18:19], 2, s[28:29]
	global_load_dword v233, v[18:19], off
	v_mov_b32_e32 v19, v159
	v_or_b32_e32 v18, v16, v83
	v_lshl_add_u64 v[18:19], v[18:19], 2, s[28:29]
	global_load_dword v234, v[18:19], off
	v_mov_b32_e32 v19, v159
	v_or_b32_e32 v18, v16, v85
	v_lshl_add_u64 v[18:19], v[18:19], 2, s[28:29]
	global_load_dword v235, v[18:19], off
	v_mov_b32_e32 v19, v159
	v_or_b32_e32 v18, v16, v87
	v_lshl_add_u64 v[18:19], v[18:19], 2, s[28:29]
	global_load_dword v236, v[18:19], off
	v_mov_b32_e32 v19, v159
	v_or_b32_e32 v18, v16, v89
	v_lshl_add_u64 v[18:19], v[18:19], 2, s[28:29]
	global_load_dword v237, v[18:19], off
	v_mov_b32_e32 v19, v159
	v_or_b32_e32 v18, v16, v91
	v_lshl_add_u64 v[18:19], v[18:19], 2, s[28:29]
	global_load_dword v238, v[18:19], off
	v_mov_b32_e32 v19, v159
	v_or_b32_e32 v18, v16, v93
	v_lshl_add_u64 v[18:19], v[18:19], 2, s[28:29]
	global_load_dword v239, v[18:19], off
	v_mov_b32_e32 v19, v159
	v_or_b32_e32 v18, v16, v95
	v_lshl_add_u64 v[18:19], v[18:19], 2, s[28:29]
	global_load_dword v240, v[18:19], off
	v_mov_b32_e32 v19, v159
	v_or_b32_e32 v18, v16, v97
	v_lshl_add_u64 v[18:19], v[18:19], 2, s[28:29]
	global_load_dword v241, v[18:19], off
	v_mov_b32_e32 v19, v159
	v_or_b32_e32 v18, v16, v99
	v_lshl_add_u64 v[18:19], v[18:19], 2, s[28:29]
	global_load_dword v242, v[18:19], off
	v_mov_b32_e32 v19, v159
	v_or_b32_e32 v18, v16, v101
	v_lshl_add_u64 v[18:19], v[18:19], 2, s[28:29]
	global_load_dword v243, v[18:19], off
	v_mov_b32_e32 v19, v159
	v_or_b32_e32 v18, v16, v103
	v_lshl_add_u64 v[18:19], v[18:19], 2, s[28:29]
	global_load_dword v244, v[18:19], off
	v_mov_b32_e32 v19, v159
	v_or_b32_e32 v18, v16, v105
	v_lshl_add_u64 v[18:19], v[18:19], 2, s[28:29]
	global_load_dword v245, v[18:19], off
	v_mov_b32_e32 v19, v159
	s_waitcnt vmcnt(0)
	v_mul_f32_e32 v18, v121, v230
	ds_write_b32 v76, v18
	v_mul_f32_e32 v18, v122, v231
	ds_write_b32 v78, v18
	v_mul_f32_e32 v18, v123, v232
	ds_write_b32 v80, v18
	v_mul_f32_e32 v18, v124, v233
	ds_write_b32 v82, v18
	v_mul_f32_e32 v18, v125, v234
	ds_write_b32 v84, v18
	v_mul_f32_e32 v18, v29, v235
	ds_write_b32 v86, v18
	v_mul_f32_e32 v18, v28, v236
	ds_write_b32 v88, v18
	v_mul_f32_e32 v18, v27, v237
	ds_write_b32 v90, v18
	v_mul_f32_e32 v18, v26, v238
	ds_write_b32 v92, v18
	v_mul_f32_e32 v18, v25, v239
	ds_write_b32 v94, v18
	v_mul_f32_e32 v18, v24, v240
	ds_write_b32 v96, v18
	v_mul_f32_e32 v18, v23, v241
	ds_write_b32 v98, v18
	v_mul_f32_e32 v18, v22, v242
	ds_write_b32 v100, v18
	v_mul_f32_e32 v18, v21, v243
	ds_write_b32 v102, v18
	v_mul_f32_e32 v18, v20, v244
	ds_write_b32 v104, v18
	v_mul_f32_e32 v17, v17, v245
	ds_write_b32 v106, v17
	v_mov_b32_e32 v17, v159
	s_waitcnt lgkmcnt(0)
	v_lshl_add_u64 v[20:21], v[16:17], 1, v[6:7]
	ds_read2_b32 v[16:17], v108 offset1:33
	s_waitcnt lgkmcnt(0)
	v_cvt_pk_bf16_f32 v16, v16, v17
	ds_read2_b32 v[18:19], v108 offset0:66 offset1:99
	s_waitcnt lgkmcnt(0)
	v_cvt_pk_bf16_f32 v17, v18, v19
	ds_read2_b32 v[18:19], v108 offset0:132 offset1:165
	s_waitcnt lgkmcnt(0)
	v_cvt_pk_bf16_f32 v18, v18, v19
	ds_read2_b32 v[22:23], v108 offset0:198 offset1:231
	s_waitcnt lgkmcnt(0)
	v_cvt_pk_bf16_f32 v19, v22, v23
	v_or_b32_e32 v22, v158, v107
	v_lshlrev_b32_e32 v22, 11, v22
	v_mov_b32_e32 v23, v159
	v_lshl_add_u64 v[22:23], v[20:21], 0, v[22:23]
	global_store_dwordx4 v[22:23], v[16:19], off
	ds_read2_b32 v[16:17], v108 offset0:8 offset1:41
	s_waitcnt lgkmcnt(0)
	v_cvt_pk_bf16_f32 v16, v16, v17
	ds_read2_b32 v[18:19], v108 offset0:74 offset1:107
	s_waitcnt lgkmcnt(0)
	v_cvt_pk_bf16_f32 v17, v18, v19
	ds_read2_b32 v[18:19], v108 offset0:140 offset1:173
	s_waitcnt lgkmcnt(0)
	v_cvt_pk_bf16_f32 v18, v18, v19
	ds_read2_b32 v[22:23], v108 offset0:206 offset1:239
	s_waitcnt lgkmcnt(0)
	v_cvt_pk_bf16_f32 v19, v22, v23
	v_or_b32_e32 v22, v158, v109
	v_lshlrev_b32_e32 v22, 11, v22
	v_mov_b32_e32 v23, v159
	v_lshl_add_u64 v[22:23], v[20:21], 0, v[22:23]
	global_store_dwordx4 v[22:23], v[16:19], off
	ds_read2_b32 v[16:17], v108 offset0:16 offset1:49
	s_waitcnt lgkmcnt(0)
	v_cvt_pk_bf16_f32 v16, v16, v17
	ds_read2_b32 v[18:19], v108 offset0:82 offset1:115
	s_waitcnt lgkmcnt(0)
	v_cvt_pk_bf16_f32 v17, v18, v19
	ds_read2_b32 v[18:19], v108 offset0:148 offset1:181
	s_waitcnt lgkmcnt(0)
	v_cvt_pk_bf16_f32 v18, v18, v19
	ds_read2_b32 v[22:23], v108 offset0:214 offset1:247
	s_waitcnt lgkmcnt(0)
	v_cvt_pk_bf16_f32 v19, v22, v23
	v_or_b32_e32 v22, v158, v110
	v_lshlrev_b32_e32 v22, 11, v22
	v_mov_b32_e32 v23, v159
	v_lshl_add_u64 v[22:23], v[20:21], 0, v[22:23]
	global_store_dwordx4 v[22:23], v[16:19], off
	ds_read2_b32 v[16:17], v108 offset0:24 offset1:57
	s_waitcnt lgkmcnt(0)
	v_cvt_pk_bf16_f32 v16, v16, v17
	ds_read2_b32 v[18:19], v108 offset0:90 offset1:123
	s_waitcnt lgkmcnt(0)
	v_cvt_pk_bf16_f32 v17, v18, v19
	ds_read2_b32 v[18:19], v108 offset0:156 offset1:189
	s_waitcnt lgkmcnt(0)
	v_cvt_pk_bf16_f32 v18, v18, v19
	ds_read2_b32 v[22:23], v108 offset0:222 offset1:255
	s_waitcnt lgkmcnt(0)
	v_cvt_pk_bf16_f32 v19, v22, v23
	v_or_b32_e32 v22, v158, v111
	v_lshlrev_b32_e32 v158, 11, v22
	v_lshl_add_u64 v[20:21], v[20:21], 0, v[158:159]
	global_store_dwordx4 v[20:21], v[16:19], off
	s_waitcnt lgkmcnt(0)
